# P8-first-weight-section-from-unit-start
# baseline (speedup 1.0000x reference)
;     template <bool EDGE> __device__ __forceinline__ void body(const f32x4 (&acc)[2][2][4][2], const pg8::Unit& u, int wr, int wc, int fr, int fq) const {
;     ...
;             const f32x4 wv0 = *(const f32x4*)(conv_w + ch), wv1 = *(const f32x4*)(conv_w + NUP + ch), wv2 = *(const f32x4*)(conv_w + 2 * NUP + ch), bv = *(const f32x4*)(conv_b + ch);
;             const f32x4 wg0 = *(const f32x4*)(conv_w + DFF + ch), wg1 = *(const f32x4*)(conv_w + NUP + DFF + ch), wg2 = *(const f32x4*)(conv_w + 2 * NUP + DFF + ch), bg = *(const f32x4*)(conv_b + DFF + ch);
.LBB0_779:
	s_mul_i32 s76, s75, 0x7e000
	s_and_b64 s[0:1], s[8:9], exec
	s_cselect_b32 s0, s76, s2
	s_lshl_b32 s77, s74, 19
	s_and_b64 s[12:13], s[8:9], exec
	v_mov_b32_e32 v12, 0
	s_cselect_b32 s1, s77, s3
	s_addk_i32 s2, 0x2080
	s_addk_i32 s3, 0x100
	s_mov_b32 s11, -2
	s_waitcnt vmcnt(0)
	v_lshl_or_b32 v128, s24, 7, v204
	v_ashrrev_i32_e32 v129, 31, v128
	v_lshlrev_b64 v[128:129], 2, v[128:129]
	v_lshl_add_u64 v[222:223], s[28:29], 0, v[128:129]
	global_load_dwordx4 v[222:225], v[222:223], off
	v_lshl_add_u64 v[226:227], s[44:45], 0, v[128:129]
	global_load_dwordx4 v[226:229], v[226:227], off
	v_lshl_add_u64 v[230:231], s[46:47], 0, v[128:129]
	global_load_dwordx4 v[230:233], v[230:231], off
	v_lshl_add_u64 v[234:235], s[30:31], 0, v[128:129]
	global_load_dwordx4 v[234:237], v[234:235], off
	v_lshl_add_u64 v[238:239], s[48:49], 0, v[128:129]
	global_load_dwordx4 v[238:241], v[238:239], off
	v_lshl_add_u64 v[242:243], s[50:51], 0, v[128:129]
	global_load_dwordx4 v[242:245], v[242:243], off
	v_lshl_add_u64 v[246:247], s[52:53], 0, v[128:129]
	global_load_dwordx4 v[246:249], v[246:247], off
	v_lshl_add_u64 v[250:251], s[54:55], 0, v[128:129]
	global_load_dwordx4 v[250:253], v[250:251], off
	ds_read_b128 v[128:131], v207
	ds_read_b128 v[132:135], v207 offset:1024
	ds_read_b128 v[136:139], v207 offset:2048
	ds_read_b128 v[140:143], v207 offset:3072
	ds_read_b128 v[144:147], v208
	ds_read_b128 v[148:151], v208 offset:1024
	ds_read_b128 v[152:155], v208 offset:2048
	ds_read_b128 v[156:159], v208 offset:3072
	s_add_i32 s12, s2, 0xffffe080
	s_cmp_eq_u32 s11, 12
	s_cselect_b32 s14, s0, s12
	s_cselect_b32 s13, s1, s3
	s_or_b32 s12, s14, 0x80
	v_add_u32_e32 v184, s2, v206
	ds_read_b128 v[164:167], v209
	ds_read_b128 v[168:171], v209 offset:1024
	ds_read_b128 v[172:175], v209 offset:2048
	ds_read_b128 v[176:179], v209 offset:3072
	ds_read_b128 v[180:183], v209 offset:4096
	ds_read_b128 v[210:213], v209 offset:5120
	ds_read_b128 v[214:217], v209 offset:6144
	ds_read_b128 v[218:221], v209 offset:7168
	s_add_i32 m0, s27, 0xc000
	s_nop 0
	global_load_lds_dwordx4 v184, s[22:23]
	v_add_u32_e32 v184, s2, v205
	s_add_i32 m0, s27, 0xe000
	s_nop 0
	global_load_lds_dwordx4 v184, s[22:23]
	s_waitcnt vmcnt(8)
	s_waitcnt lgkmcnt(0)
	s_barrier
	s_waitcnt lgkmcnt(0)
	v_mfma_f32_16x16x32_bf16 v[120:123], v[128:131], v[164:167], 0
	v_mfma_f32_16x16x32_bf16 v[56:59], v[136:139], v[164:167], 0
	v_mfma_f32_16x16x32_bf16 v[112:115], v[128:131], v[172:175], 0
	v_mfma_f32_16x16x32_bf16 v[48:51], v[136:139], v[172:175], 0
	v_mfma_f32_16x16x32_bf16 v[104:107], v[128:131], v[180:183], 0
	v_mfma_f32_16x16x32_bf16 v[40:43], v[136:139], v[180:183], 0
	v_mfma_f32_16x16x32_bf16 v[96:99], v[128:131], v[214:217], 0
	v_mfma_f32_16x16x32_bf16 v[32:35], v[136:139], v[214:217], 0
	v_mfma_f32_16x16x32_bf16 v[120:123], v[132:135], v[168:171], v[120:123]
	v_mfma_f32_16x16x32_bf16 v[56:59], v[140:143], v[168:171], v[56:59]
	v_mfma_f32_16x16x32_bf16 v[112:115], v[132:135], v[176:179], v[112:115]
	v_mfma_f32_16x16x32_bf16 v[48:51], v[140:143], v[176:179], v[48:51]
	v_mfma_f32_16x16x32_bf16 v[104:107], v[132:135], v[210:213], v[104:107]
	v_mfma_f32_16x16x32_bf16 v[40:43], v[140:143], v[210:213], v[40:43]
	v_mfma_f32_16x16x32_bf16 v[96:99], v[132:135], v[218:221], v[96:99]
	v_mfma_f32_16x16x32_bf16 v[32:35], v[140:143], v[218:221], v[32:35]
	v_mfma_f32_16x16x32_bf16 v[124:127], v[144:147], v[164:167], 0
	v_mfma_f32_16x16x32_bf16 v[60:63], v[152:155], v[164:167], 0
	v_mfma_f32_16x16x32_bf16 v[116:119], v[144:147], v[172:175], 0
	v_mfma_f32_16x16x32_bf16 v[52:55], v[152:155], v[172:175], 0
	v_mfma_f32_16x16x32_bf16 v[108:111], v[144:147], v[180:183], 0
	v_mfma_f32_16x16x32_bf16 v[44:47], v[152:155], v[180:183], 0
	v_mfma_f32_16x16x32_bf16 v[100:103], v[144:147], v[214:217], 0
	v_mfma_f32_16x16x32_bf16 v[36:39], v[152:155], v[214:217], 0
	v_mfma_f32_16x16x32_bf16 v[124:127], v[148:151], v[168:171], v[124:127]
	v_mfma_f32_16x16x32_bf16 v[60:63], v[156:159], v[168:171], v[60:63]
	v_mfma_f32_16x16x32_bf16 v[116:119], v[148:151], v[176:179], v[116:119]
	v_mfma_f32_16x16x32_bf16 v[52:55], v[156:159], v[176:179], v[52:55]
	v_mfma_f32_16x16x32_bf16 v[108:111], v[148:151], v[210:213], v[108:111]
	v_mfma_f32_16x16x32_bf16 v[44:47], v[156:159], v[210:213], v[44:47]
	v_mfma_f32_16x16x32_bf16 v[100:103], v[148:151], v[218:221], v[100:103]
	v_mfma_f32_16x16x32_bf16 v[36:39], v[156:159], v[218:221], v[36:39]
	s_barrier
	v_add_u32_e32 v184, s13, v192
	s_add_i32 s15, s71, s26
	ds_read_b128 v[164:167], v209 offset:16384
	ds_read_b128 v[168:171], v209 offset:17408
	ds_read_b128 v[172:175], v209 offset:18432
	ds_read_b128 v[176:179], v209 offset:19456
	ds_read_b128 v[180:183], v209 offset:20480
	ds_read_b128 v[210:213], v209 offset:21504
	ds_read_b128 v[214:217], v209 offset:22528
	ds_read_b128 v[218:221], v209 offset:23552
	s_mov_b32 m0, s15
	s_add_i32 s16, s72, s26
	global_load_lds_dwordx4 v184, s[36:37]
	v_add_u32_e32 v184, s13, v194
	s_add_i32 m0, s15, 0x2000
	s_add_i32 s15, s13, 0x40000
	global_load_lds_dwordx4 v184, s[36:37]
	v_add_u32_e32 v184, s15, v192
	s_mov_b32 m0, s16
	s_nop 0
	global_load_lds_dwordx4 v184, s[36:37]
	v_add_u32_e32 v184, s15, v194
	s_add_i32 m0, s16, 0x2000
	s_nop 0
	global_load_lds_dwordx4 v184, s[36:37]
	v_add_u32_e32 v184, s14, v191
	s_mov_b32 m0, s27
	s_nop 0
	global_load_lds_dwordx4 v184, s[22:23]
	v_add_u32_e32 v184, s14, v193
	s_mov_b32 m0, s33
	s_nop 0
	global_load_lds_dwordx4 v184, s[22:23]
	s_waitcnt vmcnt(8)
	s_waitcnt lgkmcnt(0)
	s_barrier
	s_waitcnt lgkmcnt(0)
	v_mfma_f32_16x16x32_bf16 v[88:91], v[128:131], v[164:167], 0
	v_mfma_f32_16x16x32_bf16 v[24:27], v[136:139], v[164:167], 0
	v_mfma_f32_16x16x32_bf16 v[72:75], v[128:131], v[172:175], 0
	v_mfma_f32_16x16x32_bf16 v[8:11], v[136:139], v[172:175], 0
	v_mfma_f32_16x16x32_bf16 v[68:71], v[128:131], v[180:183], 0
	v_mfma_f32_16x16x32_bf16 v[4:7], v[136:139], v[180:183], 0
	v_mfma_f32_16x16x32_bf16 v[64:67], v[128:131], v[214:217], 0
	v_mfma_f32_16x16x32_bf16 v[0:3], v[136:139], v[214:217], 0
	v_mfma_f32_16x16x32_bf16 v[88:91], v[132:135], v[168:171], v[88:91]
	v_mfma_f32_16x16x32_bf16 v[24:27], v[140:143], v[168:171], v[24:27]
	v_mfma_f32_16x16x32_bf16 v[72:75], v[132:135], v[176:179], v[72:75]
	v_mfma_f32_16x16x32_bf16 v[8:11], v[140:143], v[176:179], v[8:11]
	v_mfma_f32_16x16x32_bf16 v[68:71], v[132:135], v[210:213], v[68:71]
	v_mfma_f32_16x16x32_bf16 v[4:7], v[140:143], v[210:213], v[4:7]
	v_mfma_f32_16x16x32_bf16 v[64:67], v[132:135], v[218:221], v[64:67]
	v_mfma_f32_16x16x32_bf16 v[0:3], v[140:143], v[218:221], v[0:3]
	v_mfma_f32_16x16x32_bf16 v[92:95], v[144:147], v[164:167], 0
	v_mfma_f32_16x16x32_bf16 v[28:31], v[152:155], v[164:167], 0
	v_mfma_f32_16x16x32_bf16 v[76:79], v[144:147], v[172:175], 0
	v_mfma_f32_16x16x32_bf16 v[16:19], v[152:155], v[172:175], 0
	v_mfma_f32_16x16x32_bf16 v[84:87], v[144:147], v[180:183], 0
	v_mfma_f32_16x16x32_bf16 v[20:23], v[152:155], v[180:183], 0
	v_mfma_f32_16x16x32_bf16 v[80:83], v[144:147], v[214:217], 0
	v_mfma_f32_16x16x32_bf16 v[12:15], v[152:155], v[214:217], 0
	v_mfma_f32_16x16x32_bf16 v[92:95], v[148:151], v[168:171], v[92:95]
	v_mfma_f32_16x16x32_bf16 v[28:31], v[156:159], v[168:171], v[28:31]
	v_mfma_f32_16x16x32_bf16 v[76:79], v[148:151], v[176:179], v[76:79]
	v_mfma_f32_16x16x32_bf16 v[16:19], v[156:159], v[176:179], v[16:19]
	v_mfma_f32_16x16x32_bf16 v[84:87], v[148:151], v[210:213], v[84:87]
	v_mfma_f32_16x16x32_bf16 v[20:23], v[156:159], v[210:213], v[20:23]
	v_mfma_f32_16x16x32_bf16 v[80:83], v[148:151], v[218:221], v[80:83]
	v_mfma_f32_16x16x32_bf16 v[12:15], v[156:159], v[218:221], v[12:15]
	s_barrier
	s_add_i32 s15, 0, 0x18000
	s_add_i32 s16, 0, 0x1c000
	v_add_u32_e32 v140, s15, v195
	v_add_u32_e32 v156, s16, v195
	ds_read_b128 v[128:131], v140
	ds_read_b128 v[132:135], v140 offset:1024
	ds_read_b128 v[136:139], v140 offset:2048
	ds_read_b128 v[140:143], v140 offset:3072
	ds_read_b128 v[144:147], v156
	ds_read_b128 v[148:151], v156 offset:1024
	ds_read_b128 v[152:155], v156 offset:2048
	ds_read_b128 v[156:159], v156 offset:3072
	s_addk_i32 s14, 0x2000
	v_add_u32_e32 v184, s14, v191
	s_mov_b32 m0, s34
	ds_read_b128 v[164:167], v209 offset:32768
	ds_read_b128 v[168:171], v209 offset:33792
	ds_read_b128 v[172:175], v209 offset:34816
	ds_read_b128 v[176:179], v209 offset:35840
	ds_read_b128 v[180:183], v209 offset:36864
	ds_read_b128 v[210:213], v209 offset:37888
	ds_read_b128 v[214:217], v209 offset:38912
	ds_read_b128 v[218:221], v209 offset:39936
	s_nop 0
	global_load_lds_dwordx4 v184, s[22:23]
	v_add_u32_e32 v184, s14, v193
	s_mov_b32 m0, s35
	s_nop 0
	global_load_lds_dwordx4 v184, s[22:23]
	s_waitcnt vmcnt(8)
	s_waitcnt lgkmcnt(0)
	s_barrier
	s_waitcnt lgkmcnt(0)
	v_mfma_f32_16x16x32_bf16 v[120:123], v[128:131], v[164:167], v[120:123]
	v_mfma_f32_16x16x32_bf16 v[56:59], v[136:139], v[164:167], v[56:59]
	v_mfma_f32_16x16x32_bf16 v[112:115], v[128:131], v[172:175], v[112:115]
	v_mfma_f32_16x16x32_bf16 v[48:51], v[136:139], v[172:175], v[48:51]
	v_mfma_f32_16x16x32_bf16 v[104:107], v[128:131], v[180:183], v[104:107]
	v_mfma_f32_16x16x32_bf16 v[40:43], v[136:139], v[180:183], v[40:43]
	v_mfma_f32_16x16x32_bf16 v[96:99], v[128:131], v[214:217], v[96:99]
	v_mfma_f32_16x16x32_bf16 v[32:35], v[136:139], v[214:217], v[32:35]
	v_mfma_f32_16x16x32_bf16 v[120:123], v[132:135], v[168:171], v[120:123]
	v_mfma_f32_16x16x32_bf16 v[56:59], v[140:143], v[168:171], v[56:59]
	v_mfma_f32_16x16x32_bf16 v[112:115], v[132:135], v[176:179], v[112:115]
	v_mfma_f32_16x16x32_bf16 v[48:51], v[140:143], v[176:179], v[48:51]
	v_mfma_f32_16x16x32_bf16 v[104:107], v[132:135], v[210:213], v[104:107]
	v_mfma_f32_16x16x32_bf16 v[40:43], v[140:143], v[210:213], v[40:43]
	v_mfma_f32_16x16x32_bf16 v[96:99], v[132:135], v[218:221], v[96:99]
	v_mfma_f32_16x16x32_bf16 v[32:35], v[140:143], v[218:221], v[32:35]
	v_mfma_f32_16x16x32_bf16 v[124:127], v[144:147], v[164:167], v[124:127]
	v_mfma_f32_16x16x32_bf16 v[60:63], v[152:155], v[164:167], v[60:63]
	v_mfma_f32_16x16x32_bf16 v[116:119], v[144:147], v[172:175], v[116:119]
	v_mfma_f32_16x16x32_bf16 v[52:55], v[152:155], v[172:175], v[52:55]
	v_mfma_f32_16x16x32_bf16 v[108:111], v[144:147], v[180:183], v[108:111]
	v_mfma_f32_16x16x32_bf16 v[44:47], v[152:155], v[180:183], v[44:47]
	v_mfma_f32_16x16x32_bf16 v[100:103], v[144:147], v[214:217], v[100:103]
	v_mfma_f32_16x16x32_bf16 v[36:39], v[152:155], v[214:217], v[36:39]
	v_mfma_f32_16x16x32_bf16 v[124:127], v[148:151], v[168:171], v[124:127]
	v_mfma_f32_16x16x32_bf16 v[60:63], v[156:159], v[168:171], v[60:63]
	v_mfma_f32_16x16x32_bf16 v[116:119], v[148:151], v[176:179], v[116:119]
	v_mfma_f32_16x16x32_bf16 v[52:55], v[156:159], v[176:179], v[52:55]
	v_mfma_f32_16x16x32_bf16 v[108:111], v[148:151], v[210:213], v[108:111]
	v_mfma_f32_16x16x32_bf16 v[44:47], v[156:159], v[210:213], v[44:47]
	v_mfma_f32_16x16x32_bf16 v[100:103], v[148:151], v[218:221], v[100:103]
	v_mfma_f32_16x16x32_bf16 v[36:39], v[156:159], v[218:221], v[36:39]
	s_barrier
	s_or_b32 s14, s13, 0x80
	v_add_u32_e32 v184, s14, v192
	s_add_i32 s15, s15, s26
	ds_read_b128 v[164:167], v209 offset:49152
	ds_read_b128 v[168:171], v209 offset:50176
	ds_read_b128 v[172:175], v209 offset:51200
	ds_read_b128 v[176:179], v209 offset:52224
	ds_read_b128 v[180:183], v209 offset:53248
	ds_read_b128 v[210:213], v209 offset:54272
	ds_read_b128 v[214:217], v209 offset:55296
	ds_read_b128 v[218:221], v209 offset:56320
	s_mov_b32 m0, s15
	s_add_i32 s13, s13, 0x40080
	global_load_lds_dwordx4 v184, s[36:37]
	v_add_u32_e32 v184, s14, v194
	s_add_i32 m0, s15, 0x2000
	s_add_i32 s14, s16, s26
	global_load_lds_dwordx4 v184, s[36:37]
	v_add_u32_e32 v184, s13, v192
	s_mov_b32 m0, s14
	s_nop 0
	global_load_lds_dwordx4 v184, s[36:37]
	v_add_u32_e32 v184, s13, v194
	s_add_i32 m0, s14, 0x2000
	s_nop 0
	global_load_lds_dwordx4 v184, s[36:37]
	v_add_u32_e32 v184, s12, v191
	s_mov_b32 m0, s61
	s_nop 0
	global_load_lds_dwordx4 v184, s[22:23]
	v_add_u32_e32 v184, s12, v193
	s_mov_b32 m0, s63
	s_nop 0
	global_load_lds_dwordx4 v184, s[22:23]
	s_waitcnt vmcnt(8)
	s_waitcnt lgkmcnt(0)
	s_barrier
	s_waitcnt lgkmcnt(0)
	v_mfma_f32_16x16x32_bf16 v[88:91], v[128:131], v[164:167], v[88:91]
	v_mfma_f32_16x16x32_bf16 v[24:27], v[136:139], v[164:167], v[24:27]
	v_mfma_f32_16x16x32_bf16 v[72:75], v[128:131], v[172:175], v[72:75]
	v_mfma_f32_16x16x32_bf16 v[8:11], v[136:139], v[172:175], v[8:11]
	v_mfma_f32_16x16x32_bf16 v[68:71], v[128:131], v[180:183], v[68:71]
	v_mfma_f32_16x16x32_bf16 v[4:7], v[136:139], v[180:183], v[4:7]
	v_mfma_f32_16x16x32_bf16 v[64:67], v[128:131], v[214:217], v[64:67]
	v_mfma_f32_16x16x32_bf16 v[0:3], v[136:139], v[214:217], v[0:3]
	v_mfma_f32_16x16x32_bf16 v[88:91], v[132:135], v[168:171], v[88:91]
	v_mfma_f32_16x16x32_bf16 v[24:27], v[140:143], v[168:171], v[24:27]
	v_mfma_f32_16x16x32_bf16 v[72:75], v[132:135], v[176:179], v[72:75]
	v_mfma_f32_16x16x32_bf16 v[8:11], v[140:143], v[176:179], v[8:11]
	v_mfma_f32_16x16x32_bf16 v[68:71], v[132:135], v[210:213], v[68:71]
	v_mfma_f32_16x16x32_bf16 v[4:7], v[140:143], v[210:213], v[4:7]
	v_mfma_f32_16x16x32_bf16 v[64:67], v[132:135], v[218:221], v[64:67]
	v_mfma_f32_16x16x32_bf16 v[0:3], v[140:143], v[218:221], v[0:3]
	v_mfma_f32_16x16x32_bf16 v[92:95], v[144:147], v[164:167], v[92:95]
	v_mfma_f32_16x16x32_bf16 v[28:31], v[152:155], v[164:167], v[28:31]
	v_mfma_f32_16x16x32_bf16 v[76:79], v[144:147], v[172:175], v[76:79]
	v_mfma_f32_16x16x32_bf16 v[16:19], v[152:155], v[172:175], v[16:19]
	v_mfma_f32_16x16x32_bf16 v[84:87], v[144:147], v[180:183], v[84:87]
	v_mfma_f32_16x16x32_bf16 v[20:23], v[152:155], v[180:183], v[20:23]
	v_mfma_f32_16x16x32_bf16 v[80:83], v[144:147], v[214:217], v[80:83]
	v_mfma_f32_16x16x32_bf16 v[12:15], v[152:155], v[214:217], v[12:15]
	v_mfma_f32_16x16x32_bf16 v[92:95], v[148:151], v[168:171], v[92:95]
	v_mfma_f32_16x16x32_bf16 v[28:31], v[156:159], v[168:171], v[28:31]
	v_mfma_f32_16x16x32_bf16 v[76:79], v[148:151], v[176:179], v[76:79]
	v_mfma_f32_16x16x32_bf16 v[16:19], v[156:159], v[176:179], v[16:19]
	v_mfma_f32_16x16x32_bf16 v[84:87], v[148:151], v[210:213], v[84:87]
	v_mfma_f32_16x16x32_bf16 v[20:23], v[156:159], v[210:213], v[20:23]
	v_mfma_f32_16x16x32_bf16 v[80:83], v[148:151], v[218:221], v[80:83]
	v_mfma_f32_16x16x32_bf16 v[12:15], v[156:159], v[218:221], v[12:15]
	s_barrier
	s_add_i32 s11, s11, 2
	s_addk_i32 s2, 0x100
	s_addk_i32 s3, 0x100
	s_cmp_gt_u32 s11, 13
	s_cbranch_scc1 .Lpeel_done_780

;     template <bool EDGE> __device__ __forceinline__ void body(const f32x4 (&acc)[2][2][4][2], const pg8::Unit& u, int wr, int wc, int fr, int fq) const {
;     ...
;             const int ch = chb + 4 * n;
;             const f32x4 wv0 = *(const f32x4*)(conv_w + ch), wv1 = *(const f32x4*)(conv_w + NUP + ch), wv2 = *(const f32x4*)(conv_w + 2 * NUP + ch), bv = *(const f32x4*)(conv_b + ch);
;             const f32x4 wg0 = *(const f32x4*)(conv_w + DFF + ch), wg1 = *(const f32x4*)(conv_w + NUP + DFF + ch), wg2 = *(const f32x4*)(conv_w + 2 * NUP + DFF + ch), bg = *(const f32x4*)(conv_b + DFF + ch);
;             const f32x4 v7 = dpp_shr1(acc[1][0][3][n]), v6 = dpp_shr1(acc[1][0][2][n]), g7 = dpp_shr1(acc[1][1][3][n]), g6 = dpp_shr1(acc[1][1][2][n]);
; #pragma unroll
;             for (int k = 0; k < 8; ++k) {
;                 const int ai = k >> 2, m = k & 3, lr = 8 * fr + k, tau = tw0 + lr, sp = tau & 4095;
;                 const f32x4 cv = acc[ai][0][m][n], cg = acc[ai][1][m][n];
;                 const f32x4 p1v = k >= 1 ? acc[(k >= 1 ? k - 1 : 0) >> 2][0][(k >= 1 ? k - 1 : 0) & 3][n] : v7;
;                 const f32x4 p1g = k >= 1 ? acc[(k >= 1 ? k - 1 : 0) >> 2][1][(k >= 1 ? k - 1 : 0) & 3][n] : g7;
;                 const f32x4 p2v = k >= 2 ? acc[(k >= 2 ? k - 2 : 0) >> 2][0][(k >= 2 ? k - 2 : 0) & 3][n] : (k == 1 ? v7 : v6);
;                 const f32x4 p2g = k >= 2 ? acc[(k >= 2 ? k - 2 : 0) >> 2][1][(k >= 2 ? k - 2 : 0) & 3][n] : (k == 1 ? g7 : g6);
;                 f32x4 val, gat;
;                 if (EDGE) { const float m1 = sp >= 1 ? 1.f : 0.f, m2 = sp >= 2 ? 1.f : 0.f;
;                     val = bv + wv2 * cv + (wv1 * m1) * p1v + (wv0 * m2) * p2v; gat = bg + wg2 * cg + (wg1 * m1) * p1g + (wg0 * m2) * p2g; }
;                 else { val = bv + wv2 * cv + wv1 * p1v + wv0 * p2v; gat = bg + wg2 * cg + wg1 * p1g + wg0 * p2g; }
;                 const f32x2 g01 = gelu_pk((f32x2){gat[0], gat[1]}), g23 = gelu_pk((f32x2){gat[2], gat[3]});
;     __device__ __forceinline__ void operator()(const f32x4 (&acc)[2][2][4][2], const pg8::Unit& u, int wr, int wc, int fr, int fq) const {
;         const int tw0 = 252 * u.pm - 2 + 126 * wr;
;         const bool edge = (tw0 <= 1) || ((tw0 & 4095) < 2) || (((tw0 + 127) >> 12) != (tw0 >> 12));
;         if (edge) body<true>(acc, u, wr, wc, fr, fq); else body<false>(acc, u, wr, wc, fr, fq);
.LBB0_783:
	s_mul_i32 s0, s10, 0xfc
	s_add_i32 s25, s65, s0
	s_cmp_lt_i32 s25, 2
	s_cselect_b64 s[0:1], -1, 0
	s_and_b32 s2, s25, 0xffe
	s_cmp_eq_u32 s2, 0
	s_cselect_b64 s[2:3], -1, 0
	s_or_b64 s[0:1], s[0:1], s[2:3]
	s_and_b64 vcc, exec, s[0:1]
	s_cbranch_vccnz .LBB0_811
	s_add_i32 s0, s25, 0x7f
	s_xor_b32 s0, s0, s25
	s_cmpk_lt_u32 s0, 0x1000
	s_mov_b64 s[0:1], -1
	s_cbranch_scc0 .LBB0_811
	v_lshl_or_b32 v164, s24, 7, v204
	v_ashrrev_i32_e32 v165, 31, v164
	v_lshlrev_b64 v[156:157], 2, v[164:165]
	v_lshl_add_u64 v[166:167], s[28:29], 0, v[156:157]
	v_lshl_add_u64 v[132:133], s[44:45], 0, v[156:157]
	v_lshl_add_u64 v[136:137], s[46:47], 0, v[156:157]
	v_lshl_add_u64 v[168:169], s[30:31], 0, v[156:157]
	v_lshl_add_u64 v[144:145], s[48:49], 0, v[156:157]
	v_lshl_add_u64 v[148:149], s[50:51], 0, v[156:157]
	v_lshl_add_u64 v[152:153], s[52:53], 0, v[156:157]
	v_lshl_add_u64 v[156:157], s[54:55], 0, v[156:157]
	s_nop 0
	s_nop 0
	v_add_u32_e32 v165, s25, v196
	s_nop 0
	s_nop 0
	v_mov_b32_e32 v170, 0
	v_mov_b32_e32 v171, 0
	s_waitcnt vmcnt(0)
	v_mov_b64_e32 v[128:129], v[222:223]
	v_mov_b64_e32 v[130:131], v[224:225]
	v_mov_b64_e32 v[132:133], v[226:227]
	v_mov_b64_e32 v[134:135], v[228:229]
	v_mov_b64_e32 v[136:137], v[230:231]
	v_mov_b64_e32 v[138:139], v[232:233]
	v_mov_b64_e32 v[140:141], v[234:235]
	v_mov_b64_e32 v[142:143], v[236:237]
	v_mov_b64_e32 v[144:145], v[238:239]
	v_mov_b64_e32 v[146:147], v[240:241]
	v_mov_b64_e32 v[148:149], v[242:243]
	v_mov_b64_e32 v[150:151], v[244:245]
	v_mov_b64_e32 v[152:153], v[246:247]
	v_mov_b64_e32 v[154:155], v[248:249]
	v_mov_b64_e32 v[156:157], v[250:251]
	v_mov_b64_e32 v[158:159], v[252:253]
	v_mov_b32_e32 v172, 0
	v_mov_b32_e32 v173, 0
	v_mov_b32_e32 v178, 0
	v_mov_b32_e32 v179, 0
	v_mov_b32_e32 v180, 0
	v_mov_b32_e32 v181, 0
	v_mov_b32_e32 v174, 0
	v_mov_b32_e32 v175, 0
	v_mov_b32_e32 v176, 0
	v_mov_b32_e32 v177, 0
	v_mov_b32_e32 v182, 0
	v_mov_b32_e32 v183, 0
	v_mov_b32_e32 v184, 0
	v_mov_b32_e32 v185, 0
	v_cmp_gt_u32_e32 vcc, s59, v165
	v_mov_b32_dpp v170, v64 row_shr:1 row_mask:0xf bank_mask:0xf
	v_mov_b32_dpp v171, v65 row_shr:1 row_mask:0xf bank_mask:0xf
	v_mov_b32_dpp v172, v66 row_shr:1 row_mask:0xf bank_mask:0xf
	v_mov_b32_dpp v173, v67 row_shr:1 row_mask:0xf bank_mask:0xf
	v_mov_b32_dpp v178, v68 row_shr:1 row_mask:0xf bank_mask:0xf
	v_mov_b32_dpp v179, v69 row_shr:1 row_mask:0xf bank_mask:0xf
	v_mov_b32_dpp v180, v70 row_shr:1 row_mask:0xf bank_mask:0xf
	v_mov_b32_dpp v181, v71 row_shr:1 row_mask:0xf bank_mask:0xf
	v_mov_b32_dpp v174, v80 row_shr:1 row_mask:0xf bank_mask:0xf
	v_mov_b32_dpp v175, v81 row_shr:1 row_mask:0xf bank_mask:0xf
	v_mov_b32_dpp v176, v82 row_shr:1 row_mask:0xf bank_mask:0xf
	v_mov_b32_dpp v177, v83 row_shr:1 row_mask:0xf bank_mask:0xf
	v_mov_b32_dpp v182, v84 row_shr:1 row_mask:0xf bank_mask:0xf
	v_mov_b32_dpp v183, v85 row_shr:1 row_mask:0xf bank_mask:0xf
	v_mov_b32_dpp v184, v86 row_shr:1 row_mask:0xf bank_mask:0xf
	v_mov_b32_dpp v185, v87 row_shr:1 row_mask:0xf bank_mask:0xf
	s_and_b64 s[0:1], s[6:7], vcc
	v_mul_lo_u32 v210, v165, s73
	s_waitcnt vmcnt(0)
	s_and_saveexec_b64 s[2:3], s[0:1]
	s_cbranch_execz .LBB0_787
	v_pk_fma_f32 v[212:213], v[124:125], v[152:153], v[156:157]
	v_mov_b64_e32 v[222:223], s[62:63]
	v_pk_fma_f32 v[212:213], v[148:149], v[174:175], v[212:213]
	v_pk_fma_f32 v[188:189], v[126:127], v[154:155], v[158:159]
	v_pk_fma_f32 v[182:183], v[144:145], v[182:183], v[212:213]
	v_pk_fma_f32 v[188:189], v[150:151], v[176:177], v[188:189]
	v_and_b32_e32 v215, 0x7fffffff, v183
	v_and_b32_e32 v214, 0x7fffffff, v182
	v_pk_fma_f32 v[220:221], v[214:215], s[58:59], 1.0 op_sel_hi:[1,0,0]
	v_pk_mul_f32 v[218:219], v[182:183], v[182:183]
	v_rcp_f32_e32 v220, v220
	v_rcp_f32_e32 v221, v221
	v_pk_mul_f32 v[218:219], v[218:219], s[56:57] op_sel_hi:[1,0]
	v_pk_fma_f32 v[184:185], v[146:147], v[184:185], v[188:189]
	v_exp_f32_e32 v218, v218
	v_pk_fma_f32 v[224:225], v[220:221], s[60:61], v[222:223] op_sel_hi:[1,0,0]
	v_exp_f32_e32 v219, v219
	v_pk_fma_f32 v[224:225], v[220:221], v[224:225], s[64:65] op_sel_hi:[1,1,0]
	v_max_f32_e32 v188, 0, v182
	v_pk_fma_f32 v[224:225], v[220:221], v[224:225], s[66:67] op_sel_hi:[1,1,0]
	v_and_b32_e32 v213, 0x7fffffff, v185
	v_pk_fma_f32 v[224:225], v[220:221], v[224:225], s[68:69] op_sel_hi:[1,1,0]
	v_and_b32_e32 v212, 0x7fffffff, v184
	v_pk_mul_f32 v[220:221], v[220:221], v[224:225]
	v_max_f32_e32 v189, 0, v183
	v_pk_mul_f32 v[218:219], v[218:219], v[220:221]
	v_pk_mul_f32 v[216:217], v[184:185], v[184:185]
	v_pk_fma_f32 v[182:183], v[214:215], v[218:219], v[188:189] neg_lo:[1,0,0] neg_hi:[1,0,0]
	v_pk_fma_f32 v[188:189], v[212:213], s[58:59], 1.0 op_sel_hi:[1,0,0]
	v_pk_mul_f32 v[214:215], v[216:217], s[56:57] op_sel_hi:[1,0]
	v_rcp_f32_e32 v188, v188
	v_rcp_f32_e32 v189, v189
	v_exp_f32_e32 v214, v214
	v_exp_f32_e32 v215, v215
	v_pk_fma_f32 v[224:225], v[120:121], v[136:137], v[140:141]
	v_pk_fma_f32 v[216:217], v[188:189], s[60:61], v[222:223] op_sel_hi:[1,0,0]
	v_pk_fma_f32 v[224:225], v[132:133], v[170:171], v[224:225]
	v_pk_fma_f32 v[216:217], v[188:189], v[216:217], s[64:65] op_sel_hi:[1,1,0]
	v_pk_fma_f32 v[220:221], v[122:123], v[138:139], v[142:143]
	v_pk_fma_f32 v[216:217], v[188:189], v[216:217], s[66:67] op_sel_hi:[1,1,0]
	v_pk_fma_f32 v[178:179], v[128:129], v[178:179], v[224:225]
	v_pk_fma_f32 v[216:217], v[188:189], v[216:217], s[68:69] op_sel_hi:[1,1,0]
	v_pk_fma_f32 v[220:221], v[134:135], v[172:173], v[220:221]
	v_pk_mul_f32 v[188:189], v[188:189], v[216:217]
	v_pk_mul_f32 v[178:179], v[178:179], v[182:183]
	v_max_f32_e32 v182, 0, v184
	v_pk_mul_f32 v[188:189], v[214:215], v[188:189]
	v_max_f32_e32 v183, 0, v185
	v_pk_fma_f32 v[180:181], v[130:131], v[180:181], v[220:221]
	v_pk_fma_f32 v[182:183], v[212:213], v[188:189], v[182:183] neg_lo:[1,0,0] neg_hi:[1,0,0]
	v_add_lshl_u32 v165, v210, v164, 1
	v_pk_mul_f32 v[180:181], v[180:181], v[182:183]
	v_cvt_pk_bf16_f32 v178, v178, v179
	v_cvt_pk_bf16_f32 v179, v180, v181
	global_store_dwordx2 v165, v[178:179], s[40:41]
